# scan staging S2: the per-element R/KK/KD LDS reads of each 16-token group are issued together right after the lora MFMAs instead of just before each use
# baseline (speedup 1.0000x reference)
.LBB0_644:
	ds_read_b128 v[78:81], v180
	ds_read_b128 v[82:85], v180 offset:16
	s_waitcnt vmcnt(5)
	v_lshlrev_b32_e32 v88, 16, v22
	v_and_b32_e32 v89, 0xffff0000, v22
	v_lshlrev_b32_e32 v90, 16, v26
	v_and_b32_e32 v91, 0xffff0000, v26
	v_lshlrev_b32_e32 v86, 16, v18
	v_and_b32_e32 v87, 0xffff0000, v18
	v_pk_add_f32 v[88:89], v[88:89], v[90:91]
	v_lshlrev_b32_e32 v90, 16, v27
	v_pk_fma_f32 v[88:89], v[88:89], 0.5, v[86:87] op_sel_hi:[1,0,1] neg_lo:[0,0,1] neg_hi:[0,0,1]
	v_and_b32_e32 v91, 0xffff0000, v27
	s_waitcnt lgkmcnt(1)
	v_pk_fma_f32 v[78:79], v[88:89], v[78:79], v[86:87]
	v_lshlrev_b32_e32 v88, 16, v23
	v_and_b32_e32 v89, 0xffff0000, v23
	v_lshlrev_b32_e32 v86, 16, v19
	v_and_b32_e32 v87, 0xffff0000, v19
	v_pk_add_f32 v[88:89], v[88:89], v[90:91]
	s_waitcnt vmcnt(4)
	v_lshlrev_b32_e32 v90, 16, v39
	v_pk_fma_f32 v[88:89], v[88:89], 0.5, v[86:87] op_sel_hi:[1,0,1] neg_lo:[0,0,1] neg_hi:[0,0,1]
	v_and_b32_e32 v91, 0xffff0000, v39
	v_pk_fma_f32 v[80:81], v[88:89], v[80:81], v[86:87]
	ds_write_b128 v181, v[78:81]
	v_lshlrev_b32_e32 v80, 16, v24
	v_and_b32_e32 v81, 0xffff0000, v24
	v_lshlrev_b32_e32 v86, 16, v28
	v_and_b32_e32 v87, 0xffff0000, v28
	v_lshlrev_b32_e32 v78, 16, v20
	v_and_b32_e32 v79, 0xffff0000, v20
	v_pk_add_f32 v[80:81], v[80:81], v[86:87]
	v_lshlrev_b32_e32 v86, 16, v29
	v_pk_fma_f32 v[80:81], v[80:81], 0.5, v[78:79] op_sel_hi:[1,0,1] neg_lo:[0,0,1] neg_hi:[0,0,1]
	v_and_b32_e32 v87, 0xffff0000, v29
	s_waitcnt lgkmcnt(1)
	v_pk_fma_f32 v[78:79], v[80:81], v[82:83], v[78:79]
	v_lshlrev_b32_e32 v82, 16, v25
	v_and_b32_e32 v83, 0xffff0000, v25
	v_lshlrev_b32_e32 v80, 16, v21
	v_and_b32_e32 v81, 0xffff0000, v21
	v_pk_add_f32 v[82:83], v[82:83], v[86:87]
	v_lshlrev_b32_e32 v86, 16, v30
	v_pk_fma_f32 v[82:83], v[82:83], 0.5, v[80:81] op_sel_hi:[1,0,1] neg_lo:[0,0,1] neg_hi:[0,0,1]
	v_and_b32_e32 v87, 0xffff0000, v30
	v_pk_fma_f32 v[80:81], v[82:83], v[84:85], v[80:81]
	ds_write_b128 v181, v[78:81] offset:16
	ds_read_b128 v[78:81], v182
	v_lshlrev_b32_e32 v82, 16, v34
	v_and_b32_e32 v83, 0xffff0000, v34
	v_lshlrev_b32_e32 v84, 16, v38
	v_and_b32_e32 v85, 0xffff0000, v38
	v_pk_add_f32 v[82:83], v[82:83], v[84:85]
	s_waitcnt vmcnt(3)
	v_lshlrev_b32_e32 v98, 16, v47
	v_pk_fma_f32 v[88:89], v[82:83], 0.5, v[86:87] op_sel_hi:[1,0,1] neg_lo:[0,0,1] neg_hi:[0,0,1]
	ds_read_b128 v[82:85], v182 offset:16
	s_waitcnt lgkmcnt(1)
	v_pk_fma_f32 v[78:79], v[88:89], v[78:79], v[86:87]
	v_lshlrev_b32_e32 v88, 16, v35
	v_and_b32_e32 v89, 0xffff0000, v35
	v_lshlrev_b32_e32 v86, 16, v31
	v_and_b32_e32 v87, 0xffff0000, v31
	v_pk_add_f32 v[88:89], v[88:89], v[90:91]
	v_lshlrev_b32_e32 v90, 16, v42
	v_pk_fma_f32 v[88:89], v[88:89], 0.5, v[86:87] op_sel_hi:[1,0,1] neg_lo:[0,0,1] neg_hi:[0,0,1]
	v_and_b32_e32 v91, 0xffff0000, v42
	v_pk_fma_f32 v[80:81], v[88:89], v[80:81], v[86:87]
	ds_write_b128 v181, v[78:81] offset:8192
	v_lshlrev_b32_e32 v80, 16, v36
	v_and_b32_e32 v81, 0xffff0000, v36
	v_lshlrev_b32_e32 v86, 16, v40
	v_and_b32_e32 v87, 0xffff0000, v40
	v_lshlrev_b32_e32 v78, 16, v32
	v_and_b32_e32 v79, 0xffff0000, v32
	v_pk_add_f32 v[80:81], v[80:81], v[86:87]
	v_lshlrev_b32_e32 v86, 16, v41
	v_pk_fma_f32 v[80:81], v[80:81], 0.5, v[78:79] op_sel_hi:[1,0,1] neg_lo:[0,0,1] neg_hi:[0,0,1]
	v_and_b32_e32 v87, 0xffff0000, v41
	s_waitcnt lgkmcnt(1)
	v_pk_fma_f32 v[78:79], v[80:81], v[82:83], v[78:79]
	v_lshlrev_b32_e32 v82, 16, v37
	v_and_b32_e32 v83, 0xffff0000, v37
	v_lshlrev_b32_e32 v80, 16, v33
	v_and_b32_e32 v81, 0xffff0000, v33
	v_pk_add_f32 v[82:83], v[82:83], v[86:87]
	v_and_b32_e32 v99, 0xffff0000, v47
	v_pk_fma_f32 v[82:83], v[82:83], 0.5, v[80:81] op_sel_hi:[1,0,1] neg_lo:[0,0,1] neg_hi:[0,0,1]
	v_lshlrev_b32_e32 v100, 16, v51
	v_pk_fma_f32 v[80:81], v[82:83], v[84:85], v[80:81]
	ds_write_b128 v181, v[78:81] offset:8208
	ds_read_b128 v[78:81], v183
	v_lshlrev_b32_e32 v82, 16, v46
	v_and_b32_e32 v83, 0xffff0000, v46
	v_lshlrev_b32_e32 v84, 16, v50
	v_and_b32_e32 v85, 0xffff0000, v50
	v_pk_add_f32 v[86:87], v[82:83], v[84:85]
	ds_read_b128 v[82:85], v184
	v_pk_fma_f32 v[92:93], v[86:87], 0.5, v[90:91] op_sel_hi:[1,0,1] neg_lo:[0,0,1] neg_hi:[0,0,1]
	ds_read_b128 v[86:89], v183 offset:16
	s_waitcnt lgkmcnt(2)
	v_pk_fma_f32 v[78:79], v[92:93], v[78:79], v[90:91]
	v_and_b32_e32 v101, 0xffff0000, v51
	ds_read_b128 v[90:93], v184 offset:16
	s_waitcnt lgkmcnt(2)
	v_pk_mul_f32 v[94:95], v[78:79], v[82:83]
	v_lshlrev_b32_e32 v82, 16, v43
	v_and_b32_e32 v83, 0xffff0000, v43
	v_pk_add_f32 v[98:99], v[98:99], v[100:101]
	v_lshlrev_b32_e32 v102, 16, v52
	v_pk_fma_f32 v[98:99], v[98:99], 0.5, v[82:83] op_sel_hi:[1,0,1] neg_lo:[0,0,1] neg_hi:[0,0,1]
	v_and_b32_e32 v103, 0xffff0000, v52
	v_pk_fma_f32 v[80:81], v[98:99], v[80:81], v[82:83]
	v_lshlrev_b32_e32 v82, 16, v44
	v_pk_mul_f32 v[98:99], v[80:81], v[84:85]
	v_lshlrev_b32_e32 v84, 16, v48
	v_and_b32_e32 v85, 0xffff0000, v48
	v_and_b32_e32 v83, 0xffff0000, v44
	v_pk_add_f32 v[84:85], v[84:85], v[102:103]
	v_pk_mul_f32 v[96:97], v[94:95], v[94:95]
	v_pk_fma_f32 v[84:85], v[84:85], 0.5, v[82:83] op_sel_hi:[1,0,1] neg_lo:[0,0,1] neg_hi:[0,0,1]
	v_lshlrev_b32_e32 v102, 16, v49
	v_and_b32_e32 v103, 0xffff0000, v49
	v_lshlrev_b32_e32 v104, 16, v53
	v_and_b32_e32 v105, 0xffff0000, v53
	v_pk_mul_f32 v[100:101], v[98:99], v[98:99]
	s_waitcnt lgkmcnt(1)
	v_pk_fma_f32 v[82:83], v[84:85], v[86:87], v[82:83]
	v_lshlrev_b32_e32 v84, 16, v45
	v_and_b32_e32 v85, 0xffff0000, v45
	v_pk_add_f32 v[102:103], v[102:103], v[104:105]
	v_add_f32_e32 v1, v96, v97
	s_waitcnt lgkmcnt(0)
	v_pk_mul_f32 v[86:87], v[82:83], v[90:91]
	v_pk_fma_f32 v[102:103], v[102:103], 0.5, v[84:85] op_sel_hi:[1,0,1] neg_lo:[0,0,1] neg_hi:[0,0,1]
	v_add_f32_e32 v1, v1, v100
	v_pk_mul_f32 v[90:91], v[86:87], v[86:87]
	v_pk_fma_f32 v[84:85], v[102:103], v[88:89], v[84:85]
	v_add_f32_e32 v1, v1, v101
	v_pk_mul_f32 v[88:89], v[84:85], v[92:93]
	v_add_f32_e32 v1, v1, v90
	v_pk_mul_f32 v[92:93], v[88:89], v[88:89]
	v_add_f32_e32 v1, v1, v91
	v_add_f32_e32 v1, v1, v92
	v_add_f32_e32 v1, v1, v93
	s_mov_b32 s6, 0xf800000
	ds_write_b128 v181, v[78:81] offset:24576
	ds_write_b128 v181, v[82:85] offset:24592
	v_add_f32_dpp v1, v1, v1 quad_perm:[1,0,3,2] row_mask:0xf bank_mask:0xf bound_ctrl:1
	s_nop 1
	v_add_f32_dpp v1, v1, v1 quad_perm:[2,3,0,1] row_mask:0xf bank_mask:0xf bound_ctrl:1
	s_nop 1
	v_add_f32_dpp v1, v1, v1 row_half_mirror row_mask:0xf bank_mask:0xf bound_ctrl:1
	v_mul_f32_e32 v90, 0x4f800000, v1
	v_cmp_gt_f32_e32 vcc, s6, v1
	s_nop 1
	v_cndmask_b32_e32 v1, v1, v90, vcc
	v_sqrt_f32_e32 v90, v1
	s_nop 0
	v_add_u32_e32 v91, -1, v90
	v_fma_f32 v92, -v91, v90, v1
	v_cmp_ge_f32_e64 s[46:47], 0, v92
	v_add_u32_e32 v92, 1, v90
	s_nop 0
	v_cndmask_b32_e64 v91, v90, v91, s[46:47]
	v_fma_f32 v90, -v92, v90, v1
	v_cmp_lt_f32_e64 s[46:47], 0, v90
	s_nop 1
	v_cndmask_b32_e64 v90, v91, v92, s[46:47]
	v_mul_f32_e32 v91, 0x37800000, v90
	v_cndmask_b32_e32 v90, v90, v91, vcc
	v_cmp_class_f32_e32 vcc, v1, v237
	s_waitcnt vmcnt(2)
	v_and_b32_e32 v92, 0xffff0000, v57
	v_cndmask_b32_e32 v1, v90, v1, vcc
	v_max_f32_e32 v1, 0x2b8cbccc, v1
	v_div_scale_f32 v90, s[6:7], v1, v1, 1.0
	v_rcp_f32_e32 v91, v90
	s_nop 0
	v_fma_f32 v78, -v90, v91, 1.0
	v_fmac_f32_e32 v91, v78, v91
	v_div_scale_f32 v78, vcc, 1.0, v1, 1.0
	v_mul_f32_e32 v79, v78, v91
	v_fma_f32 v80, -v90, v79, v78
	v_fmac_f32_e32 v79, v80, v91
	v_fma_f32 v78, -v90, v79, v78
	v_div_fmas_f32 v78, v78, v91, v79
	v_div_fixup_f32 v82, v78, v1, 1.0
	v_pk_mul_f32 v[78:79], v[94:95], v[82:83] op_sel_hi:[1,0]
	v_pk_mul_f32 v[80:81], v[98:99], v[82:83] op_sel_hi:[1,0]
	ds_write_b128 v181, v[78:81] offset:16384
	v_pk_mul_f32 v[78:79], v[86:87], v[82:83] op_sel_hi:[1,0]
	v_pk_mul_f32 v[80:81], v[88:89], v[82:83] op_sel_hi:[1,0]
	ds_write_b128 v181, v[78:81] offset:16400
	ds_read_b128 v[78:81], v185
	ds_read_b128 v[82:85], v185 offset:16
	v_lshlrev_b32_e32 v87, 16, v58
	v_lshlrev_b32_e32 v88, 16, v62
	v_lshlrev_b32_e32 v1, 16, v54
	v_add_f32_e32 v87, v88, v87
	v_fma_f32 v87, v87, 0.5, -v1
	s_waitcnt lgkmcnt(1)
	v_fmac_f32_e32 v1, v87, v78
	v_and_b32_e32 v78, 0xffff0000, v62
	v_and_b32_e32 v87, 0xffff0000, v58
	v_and_b32_e32 v86, 0xffff0000, v54
	v_add_f32_e32 v78, v78, v87
	v_fma_f32 v78, v78, 0.5, -v86
	v_fmac_f32_e32 v86, v78, v79
	v_lshlrev_b32_e32 v78, 16, v59
	v_lshlrev_b32_e32 v79, 16, v63
	v_lshlrev_b32_e32 v87, 16, v55
	v_add_f32_e32 v78, v79, v78
	v_fma_f32 v78, v78, 0.5, -v87
	v_fmac_f32_e32 v87, v78, v80
	v_and_b32_e32 v78, 0xffff0000, v63
	v_and_b32_e32 v79, 0xffff0000, v59
	v_and_b32_e32 v88, 0xffff0000, v55
	v_add_f32_e32 v78, v78, v79
	v_fma_f32 v78, v78, 0.5, -v88
	v_fmac_f32_e32 v88, v78, v81
	v_lshlrev_b32_e32 v78, 16, v60
	v_lshlrev_b32_e32 v79, 16, v64
	v_lshlrev_b32_e32 v89, 16, v56
	v_add_f32_e32 v78, v79, v78
	v_fma_f32 v78, v78, 0.5, -v89
	s_waitcnt lgkmcnt(0)
	v_fmac_f32_e32 v89, v78, v82
	v_and_b32_e32 v78, 0xffff0000, v64
	v_and_b32_e32 v79, 0xffff0000, v60
	v_and_b32_e32 v90, 0xffff0000, v56
	v_add_f32_e32 v78, v78, v79
	v_fma_f32 v78, v78, 0.5, -v90
	v_fmac_f32_e32 v90, v78, v83
	v_lshlrev_b32_e32 v78, 16, v61
	v_lshlrev_b32_e32 v79, 16, v65
	v_add_f32_e32 v1, v1, v1
	v_lshlrev_b32_e32 v91, 16, v57
	v_add_f32_e32 v78, v79, v78
	v_mul_f32_e32 v1, 0x3fb8aa3b, v1
	v_fma_f32 v80, v78, 0.5, -v91
	v_exp_f32_e32 v78, v1
	v_add_f32_e32 v1, v86, v86
	v_mul_f32_e32 v1, 0x3fb8aa3b, v1
	v_exp_f32_e32 v79, v1
	v_fmac_f32_e32 v91, v80, v84
	v_and_b32_e32 v1, 0xffff0000, v65
	v_and_b32_e32 v80, 0xffff0000, v61
	v_pk_add_f32 v[78:79], v[78:79], 1.0 op_sel_hi:[1,0]
	v_add_f32_e32 v1, v1, v80
	v_div_scale_f32 v81, s[6:7], v79, v79, 2.0
	v_rcp_f32_e32 v82, v81
	v_fma_f32 v1, v1, 0.5, -v92
	v_fmac_f32_e32 v92, v1, v85
	v_fma_f32 v1, -v81, v82, 1.0
	v_fmac_f32_e32 v82, v1, v82
	v_div_scale_f32 v1, vcc, 2.0, v79, 2.0
	v_mul_f32_e32 v80, v1, v82
	v_fma_f32 v83, -v81, v80, v1
	v_fmac_f32_e32 v80, v83, v82
	v_div_scale_f32 v83, s[6:7], v78, v78, 2.0
	v_rcp_f32_e32 v84, v83
	v_fma_f32 v1, -v81, v80, v1
	v_div_fmas_f32 v1, v1, v82, v80
	v_add_f32_e32 v80, v87, v87
	v_add_f32_e32 v81, v88, v88
	v_mul_f32_e32 v80, 0x3fb8aa3b, v80
	v_mul_f32_e32 v81, 0x3fb8aa3b, v81
	v_div_fixup_f32 v79, v1, v79, 2.0
	v_fma_f32 v1, -v83, v84, 1.0
	v_exp_f32_e32 v80, v80
	v_exp_f32_e32 v81, v81
	v_fmac_f32_e32 v84, v1, v84
	v_div_scale_f32 v1, vcc, 2.0, v78, 2.0
	v_mul_f32_e32 v82, v1, v84
	v_fma_f32 v85, -v83, v82, v1
	v_fmac_f32_e32 v82, v85, v84
	v_pk_add_f32 v[80:81], v[80:81], 1.0 op_sel_hi:[1,0]
	v_fma_f32 v1, -v83, v82, v1
	v_div_scale_f32 v83, s[6:7], v81, v81, 2.0
	v_rcp_f32_e32 v85, v83
	v_div_fmas_f32 v1, v1, v84, v82
	v_div_fixup_f32 v78, v1, v78, 2.0
	v_pk_add_f32 v[78:79], v[78:79], 1.0 op_sel_hi:[1,0] neg_lo:[1,0] neg_hi:[1,0]
	v_fma_f32 v1, -v83, v85, 1.0
	v_fmac_f32_e32 v85, v1, v85
	v_div_scale_f32 v1, vcc, 2.0, v81, 2.0
	v_mul_f32_e32 v82, v1, v85
	v_fma_f32 v84, -v83, v82, v1
	v_fmac_f32_e32 v82, v84, v85
	v_div_scale_f32 v84, s[6:7], v80, v80, 2.0
	v_rcp_f32_e32 v86, v84
	v_fma_f32 v1, -v83, v82, v1
	v_div_fmas_f32 v1, v1, v85, v82
	v_add_f32_e32 v82, v89, v89
	v_add_f32_e32 v83, v90, v90
	v_mul_f32_e32 v82, 0x3fb8aa3b, v82
	v_mul_f32_e32 v83, 0x3fb8aa3b, v83
	v_div_fixup_f32 v81, v1, v81, 2.0
	v_fma_f32 v1, -v84, v86, 1.0
	v_exp_f32_e32 v82, v82
	v_exp_f32_e32 v83, v83
	v_fmac_f32_e32 v86, v1, v86
	v_div_scale_f32 v1, vcc, 2.0, v80, 2.0
	v_mul_f32_e32 v85, v1, v86
	v_fma_f32 v87, -v84, v85, v1
	v_fmac_f32_e32 v85, v87, v86
	v_pk_add_f32 v[82:83], v[82:83], 1.0 op_sel_hi:[1,0]
	v_fma_f32 v1, -v84, v85, v1
	v_div_scale_f32 v84, s[6:7], v83, v83, 2.0
	v_rcp_f32_e32 v87, v84
	v_div_fmas_f32 v1, v1, v86, v85
	v_div_fixup_f32 v80, v1, v80, 2.0
	v_pk_add_f32 v[80:81], v[80:81], 1.0 op_sel_hi:[1,0] neg_lo:[1,0] neg_hi:[1,0]
	v_fma_f32 v1, -v84, v87, 1.0
	v_fmac_f32_e32 v87, v1, v87
	v_div_scale_f32 v1, vcc, 2.0, v83, 2.0
	v_mul_f32_e32 v85, v1, v87
	v_fma_f32 v86, -v84, v85, v1
	v_fmac_f32_e32 v85, v86, v87
	v_div_scale_f32 v86, s[6:7], v82, v82, 2.0
	v_rcp_f32_e32 v88, v86
	v_fma_f32 v1, -v84, v85, v1
	v_div_fmas_f32 v1, v1, v87, v85
	v_add_f32_e32 v84, v91, v91
	v_add_f32_e32 v85, v92, v92
	v_mul_f32_e32 v84, 0x3fb8aa3b, v84
	v_mul_f32_e32 v85, 0x3fb8aa3b, v85
	v_div_fixup_f32 v83, v1, v83, 2.0
	v_fma_f32 v1, -v86, v88, 1.0
	v_exp_f32_e32 v84, v84
	v_exp_f32_e32 v85, v85
	v_fmac_f32_e32 v88, v1, v88
	v_div_scale_f32 v1, vcc, 2.0, v82, 2.0
	v_mul_f32_e32 v87, v1, v88
	v_fma_f32 v89, -v86, v87, v1
	v_fmac_f32_e32 v87, v89, v88
	v_pk_add_f32 v[84:85], v[84:85], 1.0 op_sel_hi:[1,0]
	v_fma_f32 v1, -v86, v87, v1
	v_div_scale_f32 v86, s[6:7], v85, v85, 2.0
	v_rcp_f32_e32 v89, v86
	v_div_fmas_f32 v1, v1, v88, v87
	v_div_fixup_f32 v82, v1, v82, 2.0
	v_pk_add_f32 v[82:83], v[82:83], 1.0 op_sel_hi:[1,0] neg_lo:[1,0] neg_hi:[1,0]
	v_fma_f32 v1, -v86, v89, 1.0
	v_fmac_f32_e32 v89, v1, v89
	v_div_scale_f32 v1, vcc, 2.0, v85, 2.0
	v_mul_f32_e32 v87, v1, v89
	v_fma_f32 v88, -v86, v87, v1
	v_fmac_f32_e32 v87, v88, v89
	v_fma_f32 v1, -v86, v87, v1
	v_div_scale_f32 v86, s[6:7], v84, v84, 2.0
	v_rcp_f32_e32 v88, v86
	v_div_fmas_f32 v1, v1, v89, v87
	v_div_fixup_f32 v85, v1, v85, 2.0
	v_cvt_pk_bf16_f32 v78, v78, v79
	v_fma_f32 v1, -v86, v88, 1.0
	v_fmac_f32_e32 v88, v1, v88
	v_div_scale_f32 v1, vcc, 2.0, v84, 2.0
	v_mul_f32_e32 v87, v1, v88
	v_fma_f32 v89, -v86, v87, v1
	v_fmac_f32_e32 v87, v89, v88
	v_fma_f32 v1, -v86, v87, v1
	v_div_fmas_f32 v1, v1, v88, v87
	v_div_fixup_f32 v84, v1, v84, 2.0
	v_pk_add_f32 v[84:85], v[84:85], 1.0 op_sel_hi:[1,0] neg_lo:[1,0] neg_hi:[1,0]
	v_cvt_pk_bf16_f32 v79, v80, v81
	v_cvt_pk_bf16_f32 v80, v82, v83
	v_cvt_pk_bf16_f32 v81, v84, v85
	ds_write_b128 v186, v[78:81] offset:57856
	ds_read_b128 v[78:81], v187
	ds_read_b128 v[82:85], v187 offset:16
	s_waitcnt vmcnt(1)
	v_lshlrev_b32_e32 v88, 16, v70
	v_and_b32_e32 v89, 0xffff0000, v70
	v_lshlrev_b32_e32 v90, 16, v74
	v_and_b32_e32 v91, 0xffff0000, v74
	v_lshlrev_b32_e32 v86, 16, v66
	v_and_b32_e32 v87, 0xffff0000, v66
	v_pk_add_f32 v[88:89], v[88:89], v[90:91]
	v_lshlrev_b32_e32 v90, 16, v75
	v_pk_fma_f32 v[88:89], v[88:89], 0.5, v[86:87] op_sel_hi:[1,0,1] neg_lo:[0,0,1] neg_hi:[0,0,1]
	v_and_b32_e32 v91, 0xffff0000, v75
	s_waitcnt lgkmcnt(1)
	v_pk_fma_f32 v[78:79], v[88:89], v[78:79], v[86:87]
	v_lshlrev_b32_e32 v88, 16, v71
	v_and_b32_e32 v89, 0xffff0000, v71
	v_lshlrev_b32_e32 v86, 16, v67
	v_and_b32_e32 v87, 0xffff0000, v67
	v_pk_add_f32 v[88:89], v[88:89], v[90:91]
	v_lshlrev_b32_e32 v90, 16, v76
	v_pk_fma_f32 v[88:89], v[88:89], 0.5, v[86:87] op_sel_hi:[1,0,1] neg_lo:[0,0,1] neg_hi:[0,0,1]
	v_and_b32_e32 v91, 0xffff0000, v76
	v_pk_fma_f32 v[80:81], v[88:89], v[80:81], v[86:87]
	v_lshlrev_b32_e32 v88, 16, v72
	v_and_b32_e32 v89, 0xffff0000, v72
	v_lshlrev_b32_e32 v86, 16, v68
	v_and_b32_e32 v87, 0xffff0000, v68
	v_pk_add_f32 v[88:89], v[88:89], v[90:91]
	v_lshlrev_b32_e32 v90, 16, v77
	v_pk_fma_f32 v[88:89], v[88:89], 0.5, v[86:87] op_sel_hi:[1,0,1] neg_lo:[0,0,1] neg_hi:[0,0,1]
	v_and_b32_e32 v91, 0xffff0000, v77
	s_waitcnt lgkmcnt(0)
	v_pk_fma_f32 v[82:83], v[88:89], v[82:83], v[86:87]
	v_lshlrev_b32_e32 v88, 16, v73
	v_and_b32_e32 v89, 0xffff0000, v73
	v_lshlrev_b32_e32 v86, 16, v69
	v_and_b32_e32 v87, 0xffff0000, v69
	v_pk_add_f32 v[88:89], v[88:89], v[90:91]
	v_cvt_pk_bf16_f32 v78, v78, v79
	v_pk_fma_f32 v[88:89], v[88:89], 0.5, v[86:87] op_sel_hi:[1,0,1] neg_lo:[0,0,1] neg_hi:[0,0,1]
	v_cvt_pk_bf16_f32 v79, v80, v81
	v_pk_fma_f32 v[84:85], v[88:89], v[84:85], v[86:87]
	v_cvt_pk_bf16_f32 v80, v82, v83
	v_cvt_pk_bf16_f32 v81, v84, v85
	ds_write_b128 v186, v[78:81] offset:62464
	s_waitcnt lgkmcnt(0)
	s_barrier
	ds_read_b128 v[78:81], v159 offset:57856
	ds_read_b128 v[82:85], v159 offset:57920
	s_waitcnt lgkmcnt(1)
	v_mfma_f32_16x16x32_bf16 v[78:81], v[78:81], v[2:5], 0
	ds_read_b128 v[86:89], v159 offset:62464
	s_waitcnt lgkmcnt(1)
	v_mfma_f32_16x16x32_bf16 v[82:85], v[82:85], v[6:9], v[78:81]
	s_nop 4
	ds_read_b128 v[78:81], v159 offset:62528
	s_waitcnt lgkmcnt(1)
	v_mfma_f32_16x16x32_bf16 v[86:89], v[86:89], v[10:13], 0
	v_add_f32_e32 v1, v173, v82
	v_mul_f32_e32 v1, 0xbfb8aa3b, v1
	v_exp_f32_e32 v1, v1
	s_waitcnt lgkmcnt(0)
	v_mfma_f32_16x16x32_bf16 v[78:81], v[78:81], v[14:17], v[86:89]
	ds_read2st64_b32 v[106:107], v193 offset1:64
	ds_read_b32 v108, v193 offset:24576
	ds_read2st64_b32 v[110:111], v195 offset1:64
	ds_read_b32 v109, v195 offset:24576
	ds_read2st64_b32 v[112:113], v196 offset1:64
	ds_read_b32 v114, v196 offset:24576
	ds_read2st64_b32 v[116:117], v197 offset1:64
	ds_read_b32 v115, v197 offset:24576
	v_add_f32_e32 v1, 1.0, v1
	v_div_scale_f32 v82, s[6:7], v1, v1, s16
	v_rcp_f32_e32 v90, v82
	s_nop 4
	v_add_f32_e32 v78, v175, v78
	v_mul_f32_e32 v78, 0xbfb8aa3b, v78
	v_exp_f32_e32 v78, v78
	v_fma_f32 v86, -v82, v90, 1.0
	v_fmac_f32_e32 v90, v86, v90
	v_div_scale_f32 v86, vcc, s16, v1, s16
	v_mul_f32_e32 v87, v86, v90
	v_fma_f32 v88, -v82, v87, v86
	v_fmac_f32_e32 v87, v88, v90
	v_add_f32_e32 v78, 1.0, v78
	v_fma_f32 v82, -v82, v87, v86
	v_div_scale_f32 v86, s[6:7], v78, v78, 1.0
	v_rcp_f32_e32 v88, v86
	v_div_fmas_f32 v82, v82, v90, v87
	v_div_fixup_f32 v1, v82, v1, s16
	v_mul_f32_e32 v1, 0x3fb8aa3b, v1
	v_fma_f32 v82, -v86, v88, 1.0
	v_fmac_f32_e32 v88, v82, v88
	v_div_scale_f32 v82, vcc, 1.0, v78, 1.0
	v_mul_f32_e32 v89, v82, v88
	v_fma_f32 v87, -v86, v89, v82
	v_fmac_f32_e32 v89, v87, v88
	v_fma_f32 v82, -v86, v89, v82
	v_div_fmas_f32 v82, v82, v88, v89
	v_div_fixup_f32 v78, v82, v78, 1.0
	v_exp_f32_e32 v1, v1
	s_waitcnt lgkmcnt(1)
	v_mul_f32_e32 v87, v107, v78
	v_add_f32_e32 v78, -1.0, v78
	v_fma_f32 v78, v176, v78, 1.0
	s_waitcnt lgkmcnt(0)
	v_mul_f32_e32 v78, v108, v78
	ds_write2st64_b32 v193, v78, v1 offset0:96 offset1:128
	v_mul_f32_e32 v1, v106, v78
	v_mul_f32_e32 v78, v177, v1
	ds_write_b32 v193, v87 offset:40960
	s_nop 0
	v_mov_b32_dpp v78, v78 quad_perm:[1,0,3,2] row_mask:0xf bank_mask:0xf bound_ctrl:1
	v_fmac_f32_e32 v78, v177, v1
	s_nop 1
	v_add_f32_dpp v1, v78, v78 quad_perm:[2,3,0,1] row_mask:0xf bank_mask:0xf bound_ctrl:1
	s_nop 1
	v_add_f32_dpp v1, v1, v1 row_half_mirror row_mask:0xf bank_mask:0xf bound_ctrl:1
	s_nop 1
	v_mov_b32_dpp v78, v1 row_mirror row_mask:0xf bank_mask:0xf bound_ctrl:1
	s_and_saveexec_b64 s[6:7], s[40:41]
	v_add_f32_e32 v1, v1, v78
	ds_write_b32 v194, v1 offset:57344
	s_or_b64 exec, exec, s[6:7]
	v_add_f32_e32 v1, v173, v83
	v_mul_f32_e32 v1, 0xbfb8aa3b, v1
	v_exp_f32_e32 v1, v1
	v_add_f32_e32 v78, v175, v79
	v_mul_f32_e32 v78, 0xbfb8aa3b, v78
	v_exp_f32_e32 v78, v78
	v_add_f32_e32 v1, 1.0, v1
	v_div_scale_f32 v79, s[6:7], v1, v1, s16
	v_rcp_f32_e32 v82, v79
	v_div_scale_f32 v83, vcc, s16, v1, s16
	v_fma_f32 v86, -v79, v82, 1.0
	v_fmac_f32_e32 v82, v86, v82
	v_mul_f32_e32 v86, v83, v82
	v_fma_f32 v87, -v79, v86, v83
	v_fmac_f32_e32 v86, v87, v82
	v_fma_f32 v79, -v79, v86, v83
	v_div_fmas_f32 v79, v79, v82, v86
	v_add_f32_e32 v82, 1.0, v78
	v_div_scale_f32 v78, s[6:7], v82, v82, 1.0
	v_rcp_f32_e32 v83, v78
	v_div_fixup_f32 v1, v79, v1, s16
	v_mul_f32_e32 v1, 0x3fb8aa3b, v1
	v_exp_f32_e32 v1, v1
	v_fma_f32 v79, -v78, v83, 1.0
	v_fmac_f32_e32 v83, v79, v83
	v_div_scale_f32 v79, vcc, 1.0, v82, 1.0
	v_mul_f32_e32 v86, v79, v83
	v_fma_f32 v87, -v78, v86, v79
	v_fmac_f32_e32 v86, v87, v83
	v_fma_f32 v87, -v78, v86, v79
	v_div_fmas_f32 v83, v87, v83, v86
	v_div_fixup_f32 v82, v83, v82, 1.0
	s_waitcnt lgkmcnt(1)
	v_mul_f32_e32 v79, v82, v111
	ds_write_b32 v195, v79 offset:40960
	v_add_f32_e32 v79, -1.0, v82
	v_fma_f32 v79, v176, v79, 1.0
	s_waitcnt lgkmcnt(1)
	v_mul_f32_e32 v79, v79, v109
	ds_write2st64_b32 v195, v79, v1 offset0:96 offset1:128
	v_mul_f32_e32 v1, v79, v110
	v_mul_f32_e32 v78, v177, v1
	s_nop 1
	v_mov_b32_dpp v78, v78 quad_perm:[1,0,3,2] row_mask:0xf bank_mask:0xf bound_ctrl:1
	v_fmac_f32_e32 v78, v177, v1
	s_nop 1
	v_add_f32_dpp v1, v78, v78 quad_perm:[2,3,0,1] row_mask:0xf bank_mask:0xf bound_ctrl:1
	s_nop 1
	v_add_f32_dpp v1, v1, v1 row_half_mirror row_mask:0xf bank_mask:0xf bound_ctrl:1
	s_nop 1
	v_mov_b32_dpp v78, v1 row_mirror row_mask:0xf bank_mask:0xf bound_ctrl:1
	s_and_saveexec_b64 s[6:7], s[40:41]
	v_add_f32_e32 v1, v1, v78
	ds_write_b32 v194, v1 offset:57348
	s_or_b64 exec, exec, s[6:7]
	v_add_f32_e32 v1, v173, v84
	v_mul_f32_e32 v1, 0xbfb8aa3b, v1
	v_exp_f32_e32 v1, v1
	v_add_f32_e32 v78, v175, v80
	v_mul_f32_e32 v78, 0xbfb8aa3b, v78
	v_exp_f32_e32 v78, v78
	v_add_f32_e32 v1, 1.0, v1
	v_div_scale_f32 v79, s[6:7], v1, v1, s16
	v_rcp_f32_e32 v80, v79
	v_div_scale_f32 v82, vcc, s16, v1, s16
	v_fma_f32 v83, -v79, v80, 1.0
	v_fmac_f32_e32 v80, v83, v80
	v_mul_f32_e32 v83, v82, v80
	v_fma_f32 v84, -v79, v83, v82
	v_fmac_f32_e32 v83, v84, v80
	v_fma_f32 v79, -v79, v83, v82
	v_div_fmas_f32 v79, v79, v80, v83
	v_add_f32_e32 v80, 1.0, v78
	v_div_scale_f32 v78, s[6:7], v80, v80, 1.0
	v_rcp_f32_e32 v82, v78
	v_div_fixup_f32 v1, v79, v1, s16
	v_mul_f32_e32 v1, 0x3fb8aa3b, v1
	v_exp_f32_e32 v1, v1
	v_fma_f32 v79, -v78, v82, 1.0
	v_fmac_f32_e32 v82, v79, v82
	v_div_scale_f32 v79, vcc, 1.0, v80, 1.0
	v_mul_f32_e32 v83, v79, v82
	v_fma_f32 v84, -v78, v83, v79
	v_fmac_f32_e32 v83, v84, v82
	v_fma_f32 v84, -v78, v83, v79
	v_div_fmas_f32 v82, v84, v82, v83
	v_div_fixup_f32 v80, v82, v80, 1.0
	s_waitcnt lgkmcnt(1)
	v_mul_f32_e32 v79, v80, v113
	ds_write_b32 v196, v79 offset:40960
	v_add_f32_e32 v79, -1.0, v80
	v_fma_f32 v79, v176, v79, 1.0
	s_waitcnt lgkmcnt(1)
	v_mul_f32_e32 v79, v79, v114
	ds_write2st64_b32 v196, v79, v1 offset0:96 offset1:128
	v_mul_f32_e32 v1, v79, v112
	v_mul_f32_e32 v78, v177, v1
	s_nop 1
	v_mov_b32_dpp v78, v78 quad_perm:[1,0,3,2] row_mask:0xf bank_mask:0xf bound_ctrl:1
	v_fmac_f32_e32 v78, v177, v1
	s_nop 1
	v_add_f32_dpp v1, v78, v78 quad_perm:[2,3,0,1] row_mask:0xf bank_mask:0xf bound_ctrl:1
	s_nop 1
	v_add_f32_dpp v1, v1, v1 row_half_mirror row_mask:0xf bank_mask:0xf bound_ctrl:1
	s_nop 1
	v_mov_b32_dpp v78, v1 row_mirror row_mask:0xf bank_mask:0xf bound_ctrl:1
	s_and_saveexec_b64 s[6:7], s[40:41]
	v_add_f32_e32 v1, v1, v78
	ds_write_b32 v194, v1 offset:57352
	s_or_b64 exec, exec, s[6:7]
	v_add_f32_e32 v1, v173, v85
	v_mul_f32_e32 v1, 0xbfb8aa3b, v1
	v_exp_f32_e32 v1, v1
	v_add_f32_e32 v78, v175, v81
	v_mul_f32_e32 v78, 0xbfb8aa3b, v78
	v_exp_f32_e32 v78, v78
	v_add_f32_e32 v1, 1.0, v1
	v_div_scale_f32 v79, s[6:7], v1, v1, s16
	v_rcp_f32_e32 v80, v79
	v_div_scale_f32 v81, vcc, s16, v1, s16
	v_fma_f32 v82, -v79, v80, 1.0
	v_fmac_f32_e32 v80, v82, v80
	v_mul_f32_e32 v82, v81, v80
	v_fma_f32 v83, -v79, v82, v81
	v_fmac_f32_e32 v82, v83, v80
	v_fma_f32 v79, -v79, v82, v81
	v_div_fmas_f32 v79, v79, v80, v82
	v_add_f32_e32 v80, 1.0, v78
	v_div_scale_f32 v78, s[6:7], v80, v80, 1.0
	v_rcp_f32_e32 v81, v78
	v_div_fixup_f32 v1, v79, v1, s16
	v_mul_f32_e32 v1, 0x3fb8aa3b, v1
	v_exp_f32_e32 v1, v1
	v_fma_f32 v79, -v78, v81, 1.0
	v_fmac_f32_e32 v81, v79, v81
	v_div_scale_f32 v79, vcc, 1.0, v80, 1.0
	v_mul_f32_e32 v82, v79, v81
	v_fma_f32 v83, -v78, v82, v79
	v_fmac_f32_e32 v82, v83, v81
	v_fma_f32 v83, -v78, v82, v79
	v_div_fmas_f32 v81, v83, v81, v82
	v_div_fixup_f32 v80, v81, v80, 1.0
	s_waitcnt lgkmcnt(1)
	v_mul_f32_e32 v79, v80, v117
	ds_write_b32 v197, v79 offset:40960
	v_add_f32_e32 v79, -1.0, v80
	v_fma_f32 v79, v176, v79, 1.0
	s_waitcnt lgkmcnt(1)
	v_mul_f32_e32 v79, v79, v115
	ds_write2st64_b32 v197, v79, v1 offset0:96 offset1:128
	v_mul_f32_e32 v1, v79, v116
	v_mul_f32_e32 v78, v177, v1
	s_nop 1
	v_mov_b32_dpp v78, v78 quad_perm:[1,0,3,2] row_mask:0xf bank_mask:0xf bound_ctrl:1
	v_fmac_f32_e32 v78, v177, v1
	s_nop 1
	v_add_f32_dpp v1, v78, v78 quad_perm:[2,3,0,1] row_mask:0xf bank_mask:0xf bound_ctrl:1
	s_nop 1
	v_add_f32_dpp v1, v1, v1 row_half_mirror row_mask:0xf bank_mask:0xf bound_ctrl:1
	s_nop 1
	v_mov_b32_dpp v78, v1 row_mirror row_mask:0xf bank_mask:0xf bound_ctrl:1
	s_and_saveexec_b64 s[6:7], s[40:41]
	v_add_f32_e32 v1, v1, v78
	ds_write_b32 v194, v1 offset:57356
	s_or_b64 exec, exec, s[6:7]
	ds_read_b128 v[82:85], v159 offset:64768
	ds_read_b128 v[78:81], v159 offset:60160
	s_waitcnt lgkmcnt(1)
	v_mfma_f32_16x16x32_bf16 v[86:89], v[82:85], v[10:13], 0
	ds_read_b128 v[82:85], v159 offset:60224
	s_waitcnt lgkmcnt(1)
	v_mfma_f32_16x16x32_bf16 v[78:81], v[78:81], v[2:5], 0
	s_waitcnt lgkmcnt(0)
	v_mfma_f32_16x16x32_bf16 v[82:85], v[82:85], v[6:9], v[78:81]
	s_nop 5
	ds_read_b128 v[78:81], v159 offset:64832
	s_nop 0
	v_add_f32_e32 v1, v173, v82
	v_mul_f32_e32 v1, 0xbfb8aa3b, v1
	v_exp_f32_e32 v1, v1
	s_waitcnt lgkmcnt(0)
	v_mfma_f32_16x16x32_bf16 v[78:81], v[78:81], v[14:17], v[86:89]
	ds_read2st64_b32 v[106:107], v198 offset1:64
	ds_read_b32 v108, v198 offset:24576
	ds_read2st64_b32 v[110:111], v199 offset1:64
	ds_read_b32 v109, v199 offset:24576
	ds_read2st64_b32 v[112:113], v200 offset1:64
	ds_read_b32 v114, v200 offset:24576
	ds_read2st64_b32 v[116:117], v201 offset1:64
	ds_read_b32 v115, v201 offset:24576
	v_add_f32_e32 v1, 1.0, v1
	v_div_scale_f32 v82, s[6:7], v1, v1, s16
	s_nop 5
	v_add_f32_e32 v78, v175, v78
	v_mul_f32_e32 v78, 0xbfb8aa3b, v78
	v_exp_f32_e32 v78, v78
	v_rcp_f32_e32 v88, v82
	v_div_scale_f32 v86, vcc, s16, v1, s16
	v_add_f32_e32 v78, 1.0, v78
	v_div_scale_f32 v87, s[6:7], v78, v78, 1.0
	v_rcp_f32_e32 v89, v87
	v_fma_f32 v91, -v82, v88, 1.0
	v_fmac_f32_e32 v88, v91, v88
	v_mul_f32_e32 v91, v86, v88
	v_fma_f32 v92, -v87, v89, 1.0
	v_fmac_f32_e32 v89, v92, v89
	v_fma_f32 v92, -v82, v91, v86
	v_fmac_f32_e32 v91, v92, v88
	v_fma_f32 v82, -v82, v91, v86
	v_div_scale_f32 v90, s[46:47], 1.0, v78, 1.0
	v_div_fmas_f32 v82, v82, v88, v91
	v_div_fixup_f32 v1, v82, v1, s16
	v_mul_f32_e32 v82, v90, v89
	v_fma_f32 v86, -v87, v82, v90
	v_fmac_f32_e32 v82, v86, v89
	v_fma_f32 v88, -v87, v82, v90
	s_mov_b64 vcc, s[46:47]
	v_div_fmas_f32 v82, v88, v89, v82
	v_div_fixup_f32 v78, v82, v78, 1.0
	v_mul_f32_e32 v1, 0x3fb8aa3b, v1
	v_exp_f32_e32 v1, v1
	s_waitcnt lgkmcnt(1)
	v_mul_f32_e32 v87, v107, v78
	v_add_f32_e32 v78, -1.0, v78
	v_fma_f32 v78, v176, v78, 1.0
	s_waitcnt lgkmcnt(0)
	v_mul_f32_e32 v78, v108, v78
	ds_write2st64_b32 v198, v78, v1 offset0:96 offset1:128
	v_mul_f32_e32 v1, v106, v78
	v_mul_f32_e32 v78, v177, v1
	ds_write_b32 v198, v87 offset:40960
	s_nop 0
	v_mov_b32_dpp v78, v78 quad_perm:[1,0,3,2] row_mask:0xf bank_mask:0xf bound_ctrl:1
	v_fmac_f32_e32 v78, v177, v1
	s_nop 1
	v_add_f32_dpp v1, v78, v78 quad_perm:[2,3,0,1] row_mask:0xf bank_mask:0xf bound_ctrl:1
	s_nop 1
	v_add_f32_dpp v1, v1, v1 row_half_mirror row_mask:0xf bank_mask:0xf bound_ctrl:1
	s_nop 1
	v_mov_b32_dpp v78, v1 row_mirror row_mask:0xf bank_mask:0xf bound_ctrl:1
	s_and_saveexec_b64 s[6:7], s[40:41]
	v_add_f32_e32 v1, v1, v78
	ds_write_b32 v194, v1 offset:57408
	s_or_b64 exec, exec, s[6:7]
	v_add_f32_e32 v1, v173, v83
	v_mul_f32_e32 v1, 0xbfb8aa3b, v1
	v_exp_f32_e32 v1, v1
	v_add_f32_e32 v78, v175, v79
	v_mul_f32_e32 v78, 0xbfb8aa3b, v78
	v_exp_f32_e32 v78, v78
	v_add_f32_e32 v1, 1.0, v1
	v_div_scale_f32 v79, s[6:7], v1, v1, s16
	v_rcp_f32_e32 v82, v79
	v_div_scale_f32 v83, vcc, s16, v1, s16
	v_fma_f32 v86, -v79, v82, 1.0
	v_fmac_f32_e32 v82, v86, v82
	v_mul_f32_e32 v86, v83, v82
	v_fma_f32 v87, -v79, v86, v83
	v_fmac_f32_e32 v86, v87, v82
	v_fma_f32 v79, -v79, v86, v83
	v_div_fmas_f32 v79, v79, v82, v86
	v_add_f32_e32 v82, 1.0, v78
	v_div_scale_f32 v78, s[6:7], v82, v82, 1.0
	v_rcp_f32_e32 v83, v78
	v_div_fixup_f32 v1, v79, v1, s16
	v_mul_f32_e32 v1, 0x3fb8aa3b, v1
	v_exp_f32_e32 v1, v1
	v_fma_f32 v79, -v78, v83, 1.0
	v_fmac_f32_e32 v83, v79, v83
	v_div_scale_f32 v79, vcc, 1.0, v82, 1.0
	v_mul_f32_e32 v86, v79, v83
	v_fma_f32 v87, -v78, v86, v79
	v_fmac_f32_e32 v86, v87, v83
	v_fma_f32 v87, -v78, v86, v79
	v_div_fmas_f32 v83, v87, v83, v86
	v_div_fixup_f32 v82, v83, v82, 1.0
	s_waitcnt lgkmcnt(1)
	v_mul_f32_e32 v79, v82, v111
	ds_write_b32 v199, v79 offset:40960
	v_add_f32_e32 v79, -1.0, v82
	v_fma_f32 v79, v176, v79, 1.0
	s_waitcnt lgkmcnt(1)
	v_mul_f32_e32 v79, v79, v109
	ds_write2st64_b32 v199, v79, v1 offset0:96 offset1:128
	v_mul_f32_e32 v1, v79, v110
	v_mul_f32_e32 v78, v177, v1
	s_nop 1
	v_mov_b32_dpp v78, v78 quad_perm:[1,0,3,2] row_mask:0xf bank_mask:0xf bound_ctrl:1
	v_fmac_f32_e32 v78, v177, v1
	s_nop 1
	v_add_f32_dpp v1, v78, v78 quad_perm:[2,3,0,1] row_mask:0xf bank_mask:0xf bound_ctrl:1
	s_nop 1
	v_add_f32_dpp v1, v1, v1 row_half_mirror row_mask:0xf bank_mask:0xf bound_ctrl:1
	s_nop 1
	v_mov_b32_dpp v78, v1 row_mirror row_mask:0xf bank_mask:0xf bound_ctrl:1
	s_and_saveexec_b64 s[6:7], s[40:41]
	v_add_f32_e32 v1, v1, v78
	ds_write_b32 v194, v1 offset:57412
	s_or_b64 exec, exec, s[6:7]
	v_add_f32_e32 v1, v173, v84
	v_mul_f32_e32 v1, 0xbfb8aa3b, v1
	v_exp_f32_e32 v1, v1
	v_add_f32_e32 v78, v175, v80
	v_mul_f32_e32 v78, 0xbfb8aa3b, v78
	v_exp_f32_e32 v78, v78
	v_add_f32_e32 v1, 1.0, v1
	v_div_scale_f32 v79, s[6:7], v1, v1, s16
	v_rcp_f32_e32 v80, v79
	v_div_scale_f32 v82, vcc, s16, v1, s16
	v_fma_f32 v83, -v79, v80, 1.0
	v_fmac_f32_e32 v80, v83, v80
	v_mul_f32_e32 v83, v82, v80
	v_fma_f32 v84, -v79, v83, v82
	v_fmac_f32_e32 v83, v84, v80
	v_fma_f32 v79, -v79, v83, v82
	v_div_fmas_f32 v79, v79, v80, v83
	v_add_f32_e32 v80, 1.0, v78
	v_div_scale_f32 v78, s[6:7], v80, v80, 1.0
	v_rcp_f32_e32 v82, v78
	v_div_fixup_f32 v1, v79, v1, s16
	v_mul_f32_e32 v1, 0x3fb8aa3b, v1
	v_exp_f32_e32 v1, v1
	v_fma_f32 v79, -v78, v82, 1.0
	v_fmac_f32_e32 v82, v79, v82
	v_div_scale_f32 v79, vcc, 1.0, v80, 1.0
	v_mul_f32_e32 v83, v79, v82
	v_fma_f32 v84, -v78, v83, v79
	v_fmac_f32_e32 v83, v84, v82
	v_fma_f32 v84, -v78, v83, v79
	v_div_fmas_f32 v82, v84, v82, v83
	v_div_fixup_f32 v80, v82, v80, 1.0
	s_waitcnt lgkmcnt(1)
	v_mul_f32_e32 v79, v80, v113
	ds_write_b32 v200, v79 offset:40960
	v_add_f32_e32 v79, -1.0, v80
	v_fma_f32 v79, v176, v79, 1.0
	s_waitcnt lgkmcnt(1)
	v_mul_f32_e32 v79, v79, v114
	ds_write2st64_b32 v200, v79, v1 offset0:96 offset1:128
	v_mul_f32_e32 v1, v79, v112
	v_mul_f32_e32 v78, v177, v1
	s_nop 1
	v_mov_b32_dpp v78, v78 quad_perm:[1,0,3,2] row_mask:0xf bank_mask:0xf bound_ctrl:1
	v_fmac_f32_e32 v78, v177, v1
	s_nop 1
	v_add_f32_dpp v1, v78, v78 quad_perm:[2,3,0,1] row_mask:0xf bank_mask:0xf bound_ctrl:1
	s_nop 1
	v_add_f32_dpp v1, v1, v1 row_half_mirror row_mask:0xf bank_mask:0xf bound_ctrl:1
	s_nop 1
	v_mov_b32_dpp v78, v1 row_mirror row_mask:0xf bank_mask:0xf bound_ctrl:1
	s_and_saveexec_b64 s[6:7], s[40:41]
	v_add_f32_e32 v1, v1, v78
	ds_write_b32 v194, v1 offset:57416
	s_or_b64 exec, exec, s[6:7]
	v_add_f32_e32 v1, v173, v85
	v_mul_f32_e32 v1, 0xbfb8aa3b, v1
	v_exp_f32_e32 v1, v1
	v_add_f32_e32 v78, v175, v81
	v_mul_f32_e32 v78, 0xbfb8aa3b, v78
	v_exp_f32_e32 v78, v78
	v_add_f32_e32 v1, 1.0, v1
	v_div_scale_f32 v79, s[6:7], v1, v1, s16
	v_rcp_f32_e32 v80, v79
	v_div_scale_f32 v81, vcc, s16, v1, s16
	v_fma_f32 v82, -v79, v80, 1.0
	v_fmac_f32_e32 v80, v82, v80
	v_mul_f32_e32 v82, v81, v80
	v_fma_f32 v83, -v79, v82, v81
	v_fmac_f32_e32 v82, v83, v80
	v_fma_f32 v79, -v79, v82, v81
	v_div_fmas_f32 v79, v79, v80, v82
	v_add_f32_e32 v80, 1.0, v78
	v_div_scale_f32 v78, s[6:7], v80, v80, 1.0
	v_rcp_f32_e32 v81, v78
	v_div_fixup_f32 v1, v79, v1, s16
	v_mul_f32_e32 v1, 0x3fb8aa3b, v1
	v_exp_f32_e32 v1, v1
	v_fma_f32 v79, -v78, v81, 1.0
	v_fmac_f32_e32 v81, v79, v81
	v_div_scale_f32 v79, vcc, 1.0, v80, 1.0
	v_mul_f32_e32 v82, v79, v81
	v_fma_f32 v83, -v78, v82, v79
	v_fmac_f32_e32 v82, v83, v81
	v_fma_f32 v83, -v78, v82, v79
	v_div_fmas_f32 v81, v83, v81, v82
	v_div_fixup_f32 v80, v81, v80, 1.0
	s_waitcnt lgkmcnt(1)
	v_mul_f32_e32 v79, v80, v117
	ds_write_b32 v201, v79 offset:40960
	v_add_f32_e32 v79, -1.0, v80
	v_fma_f32 v79, v176, v79, 1.0
	s_waitcnt lgkmcnt(1)
	v_mul_f32_e32 v79, v79, v115
	ds_write2st64_b32 v201, v79, v1 offset0:96 offset1:128
	v_mul_f32_e32 v1, v79, v116
	v_mul_f32_e32 v78, v177, v1
	s_nop 1
	v_mov_b32_dpp v78, v78 quad_perm:[1,0,3,2] row_mask:0xf bank_mask:0xf bound_ctrl:1
	v_fmac_f32_e32 v78, v177, v1
	s_nop 1
	v_add_f32_dpp v1, v78, v78 quad_perm:[2,3,0,1] row_mask:0xf bank_mask:0xf bound_ctrl:1
	s_nop 1
	v_add_f32_dpp v1, v1, v1 row_half_mirror row_mask:0xf bank_mask:0xf bound_ctrl:1
	s_nop 1
	v_mov_b32_dpp v78, v1 row_mirror row_mask:0xf bank_mask:0xf bound_ctrl:1
	s_and_saveexec_b64 s[6:7], s[40:41]
	v_add_f32_e32 v1, v1, v78
	ds_write_b32 v194, v1 offset:57420
	s_or_b64 exec, exec, s[6:7]
	s_add_i32 s10, s1, 1
	s_cmpk_eq_i32 s1, 0x47
	s_cbranch_scc1 .LBB0_682
	s_add_i32 s11, s1, -7
	s_cmp_gt_u32 s1, 6
	s_cselect_b64 s[6:7], -1, 0
	s_and_b64 s[12:13], s[6:7], exec
	s_cselect_b32 s11, s11, s10
	s_cselect_b32 s12, 0x100, 0
	s_cselect_b32 s13, 63, 7
	s_add_i32 s14, s12, s79
	s_sub_i32 s15, s13, s11
	s_and_b64 s[12:13], s[50:51], exec
	s_cselect_b32 s11, s11, s15
	v_lshl_add_u32 v1, s11, 5, v178
	v_add_u32_e32 v18, s14, v1
	v_mad_i64_i32 v[54:55], s[12:13], v18, s17, v[160:161]
	s_mov_b32 s53, s9
	v_lshl_add_u64 v[56:57], v[54:55], 0, s[52:53]
	global_load_dwordx4 v[18:21], v[56:57], off offset:2880
	v_mov_b32_e32 v28, v0
	v_mov_b32_e32 v29, v0
	v_cmp_lt_i32_e64 s[46:47], 0, v1
	v_mov_b64_e32 v[24:25], v[28:29]
	v_mov_b64_e32 v[22:23], v[28:29]
	s_and_saveexec_b64 s[12:13], s[46:47]
	s_cbranch_execz .LBB0_663
	v_add_co_u32_e32 v22, vcc, 0xfffff000, v56
	s_nop 1
	v_addc_co_u32_e32 v23, vcc, -1, v57, vcc
	global_load_dwordx4 v[22:25], v[22:23], off offset:-3008
